# v59 + GEMM unit headers of P1/P3/P4/P5/P6: redundant full vmcnt(0) drains removed (no VMEM load targets the accumulator registers; P8-P10 headers never had them); attention loop tails: add+compare fol
# baseline (speedup 1.0000x reference)
.LBB0_219:
	s_ashr_i32 s45, s44, 31
	s_lshl_b64 s[46:47], s[44:45], 19
	s_add_u32 s46, s14, s46
	s_addc_u32 s47, s15, s47
	s_and_b64 s[48:49], s[6:7], exec
	s_cselect_b32 s9, s47, s51
	s_cselect_b32 s11, s46, s50
	s_ashr_i32 s43, s42, 31
	s_lshl_b64 s[48:49], s[42:43], 19
	s_add_u32 s48, s27, s48
	s_addc_u32 s49, s29, s49
	s_and_b64 s[54:55], s[6:7], exec
	s_cselect_b32 s20, s49, s53
	s_cselect_b32 s33, s48, s52
	s_add_u32 s50, s50, 0x40080
	s_addc_u32 s51, s51, 0
	s_add_u32 s43, s52, 0x100
	s_addc_u32 s45, s53, 0
	s_mov_b32 s66, -2
	v_mov_b64_e32 v[0:1], 0
	s_waitcnt lgkmcnt(0)
	v_mov_b64_e32 v[2:3], 0
	v_mov_b64_e32 v[4:5], 0
	v_mov_b64_e32 v[6:7], 0
	v_mov_b64_e32 v[16:17], 0
	v_mov_b64_e32 v[18:19], 0
	v_mov_b64_e32 v[20:21], 0
	v_mov_b64_e32 v[22:23], 0
	v_mov_b64_e32 v[32:33], 0
	v_mov_b64_e32 v[34:35], 0
	v_mov_b64_e32 v[36:37], 0
	v_mov_b64_e32 v[38:39], 0
	v_mov_b64_e32 v[48:49], 0
	v_mov_b64_e32 v[50:51], 0
	v_mov_b64_e32 v[52:53], 0
	v_mov_b64_e32 v[54:55], 0
	v_mov_b64_e32 v[8:9], 0
	v_mov_b64_e32 v[10:11], 0
	v_mov_b64_e32 v[12:13], 0
	v_mov_b64_e32 v[14:15], 0
	v_mov_b64_e32 v[24:25], 0
	v_mov_b64_e32 v[26:27], 0
	v_mov_b64_e32 v[28:29], 0
	v_mov_b64_e32 v[30:31], 0
	v_mov_b64_e32 v[40:41], 0
	v_mov_b64_e32 v[42:43], 0
	v_mov_b64_e32 v[44:45], 0
	v_mov_b64_e32 v[46:47], 0
	v_mov_b64_e32 v[56:57], 0
	v_mov_b64_e32 v[58:59], 0
	v_mov_b64_e32 v[60:61], 0
	v_mov_b64_e32 v[62:63], 0
	v_mov_b64_e32 v[64:65], 0
	v_mov_b64_e32 v[66:67], 0
	v_mov_b64_e32 v[68:69], 0
	v_mov_b64_e32 v[70:71], 0
	v_mov_b64_e32 v[80:81], 0
	v_mov_b64_e32 v[82:83], 0
	v_mov_b64_e32 v[84:85], 0
	v_mov_b64_e32 v[86:87], 0
	v_mov_b64_e32 v[96:97], 0
	v_mov_b64_e32 v[98:99], 0
	v_mov_b64_e32 v[100:101], 0
	v_mov_b64_e32 v[102:103], 0
	v_mov_b64_e32 v[112:113], 0
	v_mov_b64_e32 v[114:115], 0
	v_mov_b64_e32 v[116:117], 0
	v_mov_b64_e32 v[118:119], 0
	v_mov_b64_e32 v[72:73], 0
	v_mov_b64_e32 v[74:75], 0
	v_mov_b64_e32 v[76:77], 0
	v_mov_b64_e32 v[78:79], 0
	v_mov_b64_e32 v[88:89], 0
	v_mov_b64_e32 v[90:91], 0
	v_mov_b64_e32 v[92:93], 0
	v_mov_b64_e32 v[94:95], 0
	v_mov_b64_e32 v[104:105], 0
	v_mov_b64_e32 v[106:107], 0
	v_mov_b64_e32 v[108:109], 0
	v_mov_b64_e32 v[110:111], 0
	v_mov_b64_e32 v[120:121], 0
	v_mov_b64_e32 v[122:123], 0
	v_mov_b64_e32 v[124:125], 0
	v_mov_b64_e32 v[126:127], 0
	s_cmp_lg_u32 s90, 0
	s_cbranch_scc0 .Lkl_nobar_0
	s_barrier
	s_mov_b32 s90, 0

.LBB0_400:
	s_ashr_i32 s35, s34, 31
	s_lshl_b64 s[36:37], s[34:35], 20
	s_add_u32 s36, s14, s36
	s_addc_u32 s37, s15, s37
	s_and_b64 s[38:39], s[8:9], exec
	s_cselect_b32 s35, s37, s43
	s_cselect_b32 s41, s36, s42
	s_ashr_i32 s31, s30, 31
	s_lshl_b64 s[38:39], s[30:31], 20
	s_add_u32 s38, s20, s38
	s_addc_u32 s39, s25, s39
	s_and_b64 s[44:45], s[8:9], exec
	s_cselect_b32 s31, s39, s5
	s_cselect_b32 s56, s38, s4
	s_add_u32 s42, s42, 0x80080
	s_addc_u32 s43, s43, 0
	s_add_u32 s57, s4, 0x100
	s_addc_u32 s58, s5, 0
	s_mov_b32 s59, -2
	s_waitcnt lgkmcnt(0)
	v_mov_b64_e32 v[0:1], 0
	v_mov_b64_e32 v[2:3], 0
	v_mov_b64_e32 v[4:5], 0
	v_mov_b64_e32 v[6:7], 0
	v_mov_b64_e32 v[16:17], 0
	v_mov_b64_e32 v[18:19], 0
	v_mov_b64_e32 v[20:21], 0
	v_mov_b64_e32 v[22:23], 0
	v_mov_b64_e32 v[32:33], 0
	v_mov_b64_e32 v[34:35], 0
	v_mov_b64_e32 v[36:37], 0
	v_mov_b64_e32 v[38:39], 0
	v_mov_b64_e32 v[48:49], 0
	v_mov_b64_e32 v[50:51], 0
	v_mov_b64_e32 v[52:53], 0
	v_mov_b64_e32 v[54:55], 0
	v_mov_b64_e32 v[8:9], 0
	v_mov_b64_e32 v[10:11], 0
	v_mov_b64_e32 v[12:13], 0
	v_mov_b64_e32 v[14:15], 0
	v_mov_b64_e32 v[24:25], 0
	v_mov_b64_e32 v[26:27], 0
	v_mov_b64_e32 v[28:29], 0
	v_mov_b64_e32 v[30:31], 0
	v_mov_b64_e32 v[40:41], 0
	v_mov_b64_e32 v[42:43], 0
	v_mov_b64_e32 v[44:45], 0
	v_mov_b64_e32 v[46:47], 0
	v_mov_b64_e32 v[56:57], 0
	v_mov_b64_e32 v[58:59], 0
	v_mov_b64_e32 v[60:61], 0
	v_mov_b64_e32 v[62:63], 0
	v_mov_b64_e32 v[64:65], 0
	v_mov_b64_e32 v[66:67], 0
	v_mov_b64_e32 v[68:69], 0
	v_mov_b64_e32 v[70:71], 0
	v_mov_b64_e32 v[80:81], 0
	v_mov_b64_e32 v[82:83], 0
	v_mov_b64_e32 v[84:85], 0
	v_mov_b64_e32 v[86:87], 0
	v_mov_b64_e32 v[96:97], 0
	v_mov_b64_e32 v[98:99], 0
	v_mov_b64_e32 v[100:101], 0
	v_mov_b64_e32 v[102:103], 0
	v_mov_b64_e32 v[112:113], 0
	v_mov_b64_e32 v[114:115], 0
	v_mov_b64_e32 v[116:117], 0
	v_mov_b64_e32 v[118:119], 0
	v_mov_b64_e32 v[72:73], 0
	v_mov_b64_e32 v[74:75], 0
	v_mov_b64_e32 v[76:77], 0
	v_mov_b64_e32 v[78:79], 0
	v_mov_b64_e32 v[88:89], 0
	v_mov_b64_e32 v[90:91], 0
	v_mov_b64_e32 v[92:93], 0
	v_mov_b64_e32 v[94:95], 0
	v_mov_b64_e32 v[104:105], 0
	v_mov_b64_e32 v[106:107], 0
	v_mov_b64_e32 v[108:109], 0
	v_mov_b64_e32 v[110:111], 0
	v_mov_b64_e32 v[120:121], 0
	v_mov_b64_e32 v[122:123], 0
	v_mov_b64_e32 v[124:125], 0
	v_mov_b64_e32 v[126:127], 0
	s_cmp_lg_u32 s90, 0
	s_cbranch_scc0 .Lkl_nobar_1
	s_barrier
	s_mov_b32 s90, 0

.LBB0_482:
	s_ashr_i32 s37, s36, 31
	s_lshl_b64 s[12:13], s[36:37], 19
	s_add_u32 s38, s14, s12
	s_addc_u32 s39, s15, s13
	s_and_b64 s[12:13], s[6:7], exec
	s_cselect_b32 s9, s39, s11
	s_cselect_b32 s37, s38, s10
	s_ashr_i32 s35, s34, 31
	s_lshl_b64 s[12:13], s[34:35], 19
	s_add_u32 s40, s20, s12
	s_addc_u32 s41, s22, s13
	s_and_b64 s[12:13], s[6:7], exec
	s_cselect_b32 s35, s41, s5
	s_cselect_b32 s53, s40, s4
	s_add_u32 s10, s10, 0x40080
	s_addc_u32 s11, s11, 0
	s_add_u32 s54, s4, 0x100
	s_addc_u32 s55, s5, 0
	s_mov_b32 s56, -2
	v_mov_b64_e32 v[0:1], 0
	v_mov_b64_e32 v[2:3], 0
	v_mov_b64_e32 v[8:9], 0
	v_mov_b64_e32 v[10:11], 0
	v_mov_b64_e32 v[16:17], 0
	v_mov_b64_e32 v[18:19], 0
	v_mov_b64_e32 v[24:25], 0
	v_mov_b64_e32 v[26:27], 0
	v_mov_b64_e32 v[32:33], 0
	v_mov_b64_e32 v[34:35], 0
	v_mov_b64_e32 v[40:41], 0
	v_mov_b64_e32 v[42:43], 0
	v_mov_b64_e32 v[48:49], 0
	v_mov_b64_e32 v[50:51], 0
	v_mov_b64_e32 v[56:57], 0
	v_mov_b64_e32 v[58:59], 0
	v_mov_b64_e32 v[4:5], 0
	v_mov_b64_e32 v[6:7], 0
	v_mov_b64_e32 v[12:13], 0
	v_mov_b64_e32 v[14:15], 0
	v_mov_b64_e32 v[20:21], 0
	v_mov_b64_e32 v[22:23], 0
	v_mov_b64_e32 v[28:29], 0
	v_mov_b64_e32 v[30:31], 0
	v_mov_b64_e32 v[36:37], 0
	v_mov_b64_e32 v[38:39], 0
	v_mov_b64_e32 v[44:45], 0
	v_mov_b64_e32 v[46:47], 0
	v_mov_b64_e32 v[52:53], 0
	v_mov_b64_e32 v[54:55], 0
	v_mov_b64_e32 v[60:61], 0
	v_mov_b64_e32 v[62:63], 0
	v_mov_b64_e32 v[64:65], 0
	v_mov_b64_e32 v[66:67], 0
	v_mov_b64_e32 v[72:73], 0
	v_mov_b64_e32 v[74:75], 0
	v_mov_b64_e32 v[80:81], 0
	v_mov_b64_e32 v[82:83], 0
	v_mov_b64_e32 v[88:89], 0
	v_mov_b64_e32 v[90:91], 0
	v_mov_b64_e32 v[96:97], 0
	v_mov_b64_e32 v[98:99], 0
	v_mov_b64_e32 v[104:105], 0
	v_mov_b64_e32 v[106:107], 0
	v_mov_b64_e32 v[112:113], 0
	v_mov_b64_e32 v[114:115], 0
	v_mov_b64_e32 v[120:121], 0
	v_mov_b64_e32 v[122:123], 0
	v_mov_b64_e32 v[68:69], 0
	v_mov_b64_e32 v[70:71], 0
	v_mov_b64_e32 v[76:77], 0
	v_mov_b64_e32 v[78:79], 0
	v_mov_b64_e32 v[84:85], 0
	v_mov_b64_e32 v[86:87], 0
	v_mov_b64_e32 v[92:93], 0
	v_mov_b64_e32 v[94:95], 0
	v_mov_b64_e32 v[100:101], 0
	v_mov_b64_e32 v[102:103], 0
	v_mov_b64_e32 v[108:109], 0
	v_mov_b64_e32 v[110:111], 0
	v_mov_b64_e32 v[116:117], 0
	v_mov_b64_e32 v[118:119], 0
	v_mov_b64_e32 v[124:125], 0
	v_mov_b64_e32 v[126:127], 0
	s_cmp_lg_u32 s90, 0
	s_cbranch_scc0 .Lkl_nobar_2
	s_barrier
	s_mov_b32 s90, 0

.LBB0_558:
	s_add_u32 s55, s4, 0x100
	s_addc_u32 s56, s5, 0
	s_mov_b32 s57, -2
	s_waitcnt lgkmcnt(0)
	v_mov_b64_e32 v[0:1], 0
	v_mov_b64_e32 v[2:3], 0
	v_mov_b64_e32 v[4:5], 0
	v_mov_b64_e32 v[6:7], 0
	v_mov_b64_e32 v[16:17], 0
	v_mov_b64_e32 v[18:19], 0
	v_mov_b64_e32 v[20:21], 0
	v_mov_b64_e32 v[22:23], 0
	v_mov_b64_e32 v[32:33], 0
	v_mov_b64_e32 v[34:35], 0
	v_mov_b64_e32 v[36:37], 0
	v_mov_b64_e32 v[38:39], 0
	v_mov_b64_e32 v[48:49], 0
	v_mov_b64_e32 v[50:51], 0
	v_mov_b64_e32 v[52:53], 0
	v_mov_b64_e32 v[54:55], 0
	v_mov_b64_e32 v[8:9], 0
	v_mov_b64_e32 v[10:11], 0
	v_mov_b64_e32 v[12:13], 0
	v_mov_b64_e32 v[14:15], 0
	v_mov_b64_e32 v[24:25], 0
	v_mov_b64_e32 v[26:27], 0
	v_mov_b64_e32 v[28:29], 0
	v_mov_b64_e32 v[30:31], 0
	v_mov_b64_e32 v[40:41], 0
	v_mov_b64_e32 v[42:43], 0
	v_mov_b64_e32 v[44:45], 0
	v_mov_b64_e32 v[46:47], 0
	v_mov_b64_e32 v[56:57], 0
	v_mov_b64_e32 v[58:59], 0
	v_mov_b64_e32 v[60:61], 0
	v_mov_b64_e32 v[62:63], 0
	v_mov_b64_e32 v[64:65], 0
	v_mov_b64_e32 v[66:67], 0
	v_mov_b64_e32 v[68:69], 0
	v_mov_b64_e32 v[70:71], 0
	v_mov_b64_e32 v[80:81], 0
	v_mov_b64_e32 v[82:83], 0
	v_mov_b64_e32 v[84:85], 0
	v_mov_b64_e32 v[86:87], 0
	v_mov_b64_e32 v[96:97], 0
	v_mov_b64_e32 v[98:99], 0
	v_mov_b64_e32 v[100:101], 0
	v_mov_b64_e32 v[102:103], 0
	v_mov_b64_e32 v[112:113], 0
	v_mov_b64_e32 v[114:115], 0
	v_mov_b64_e32 v[116:117], 0
	v_mov_b64_e32 v[118:119], 0
	v_mov_b64_e32 v[72:73], 0
	v_mov_b64_e32 v[74:75], 0
	v_mov_b64_e32 v[76:77], 0
	v_mov_b64_e32 v[78:79], 0
	v_mov_b64_e32 v[88:89], 0
	v_mov_b64_e32 v[90:91], 0
	v_mov_b64_e32 v[92:93], 0
	v_mov_b64_e32 v[94:95], 0
	v_mov_b64_e32 v[104:105], 0
	v_mov_b64_e32 v[106:107], 0
	v_mov_b64_e32 v[108:109], 0
	v_mov_b64_e32 v[110:111], 0
	v_mov_b64_e32 v[120:121], 0
	v_mov_b64_e32 v[122:123], 0
	v_mov_b64_e32 v[124:125], 0
	v_mov_b64_e32 v[126:127], 0
	s_cmp_lg_u32 s90, 0
	s_cbranch_scc0 .Lkl_nobar_3
	s_barrier
	s_mov_b32 s90, 0

.LBB0_642:
	s_ashr_i32 s41, s40, 31
	s_lshl_b64 s[42:43], s[40:41], 19
	s_add_u32 s42, s14, s42
	s_addc_u32 s43, s15, s43
	s_and_b64 s[44:45], s[10:11], exec
	s_cselect_b32 s13, s43, s23
	s_cselect_b32 s17, s42, s22
	s_ashr_i32 s39, s38, 31
	s_lshl_b64 s[44:45], s[38:39], 19
	s_add_u32 s44, s20, s44
	s_addc_u32 s45, s25, s45
	s_and_b64 s[46:47], s[10:11], exec
	s_cselect_b32 s33, s45, s5
	s_cselect_b32 s39, s44, s4
	s_add_u32 s22, s22, 0x40080
	s_addc_u32 s23, s23, 0
	s_add_u32 s41, s4, 0x100
	s_addc_u32 s62, s5, 0
	s_mov_b32 s63, -2
	v_mov_b64_e32 v[0:1], 0
	v_mov_b64_e32 v[2:3], 0
	v_mov_b64_e32 v[4:5], 0
	v_mov_b64_e32 v[6:7], 0
	v_mov_b64_e32 v[16:17], 0
	v_mov_b64_e32 v[18:19], 0
	v_mov_b64_e32 v[20:21], 0
	v_mov_b64_e32 v[22:23], 0
	v_mov_b64_e32 v[32:33], 0
	v_mov_b64_e32 v[34:35], 0
	v_mov_b64_e32 v[36:37], 0
	v_mov_b64_e32 v[38:39], 0
	v_mov_b64_e32 v[48:49], 0
	v_mov_b64_e32 v[50:51], 0
	v_mov_b64_e32 v[52:53], 0
	v_mov_b64_e32 v[54:55], 0
	v_mov_b64_e32 v[8:9], 0
	v_mov_b64_e32 v[10:11], 0
	v_mov_b64_e32 v[12:13], 0
	v_mov_b64_e32 v[14:15], 0
	v_mov_b64_e32 v[24:25], 0
	v_mov_b64_e32 v[26:27], 0
	v_mov_b64_e32 v[28:29], 0
	v_mov_b64_e32 v[30:31], 0
	v_mov_b64_e32 v[40:41], 0
	v_mov_b64_e32 v[42:43], 0
	v_mov_b64_e32 v[44:45], 0
	v_mov_b64_e32 v[46:47], 0
	v_mov_b64_e32 v[56:57], 0
	v_mov_b64_e32 v[58:59], 0
	v_mov_b64_e32 v[60:61], 0
	v_mov_b64_e32 v[62:63], 0
	v_mov_b64_e32 v[64:65], 0
	v_mov_b64_e32 v[66:67], 0
	v_mov_b64_e32 v[68:69], 0
	v_mov_b64_e32 v[70:71], 0
	v_mov_b64_e32 v[80:81], 0
	v_mov_b64_e32 v[82:83], 0
	v_mov_b64_e32 v[84:85], 0
	v_mov_b64_e32 v[86:87], 0
	v_mov_b64_e32 v[96:97], 0
	v_mov_b64_e32 v[98:99], 0
	v_mov_b64_e32 v[100:101], 0
	v_mov_b64_e32 v[102:103], 0
	v_mov_b64_e32 v[112:113], 0
	v_mov_b64_e32 v[114:115], 0
	v_mov_b64_e32 v[116:117], 0
	v_mov_b64_e32 v[118:119], 0
	v_mov_b64_e32 v[72:73], 0
	v_mov_b64_e32 v[74:75], 0
	v_mov_b64_e32 v[76:77], 0
	v_mov_b64_e32 v[78:79], 0
	v_mov_b64_e32 v[88:89], 0
	v_mov_b64_e32 v[90:91], 0
	v_mov_b64_e32 v[92:93], 0
	v_mov_b64_e32 v[94:95], 0
	v_mov_b64_e32 v[104:105], 0
	v_mov_b64_e32 v[106:107], 0
	v_mov_b64_e32 v[108:109], 0
	v_mov_b64_e32 v[110:111], 0
	v_mov_b64_e32 v[120:121], 0
	v_mov_b64_e32 v[122:123], 0
	v_mov_b64_e32 v[124:125], 0
	v_mov_b64_e32 v[126:127], 0
	s_cmp_lg_u32 s90, 0
	s_cbranch_scc0 .Lkl_nobar_4
	s_barrier
	s_mov_b32 s90, 0

.LBB0_810:
	s_add_i32 s61, s61, 2
	s_addk_i32 s14, 0x4000
	s_add_u32 s92, s92, 0x40000
	s_addc_u32 s93, s93, 0
	s_add_i32 s31, s31, 2
	v_cvt_pk_bf16_f32 v176, v114, v115
	v_cvt_pk_bf16_f32 v177, v116, v117
	v_cvt_pk_bf16_f32 v178, v118, v119
	v_cvt_pk_bf16_f32 v179, v120, v121
	v_add_f32_e32 v213, v192, v122
	s_cmp_le_i32 s29, s71
	v_add_u32_e32 v187, 0x80, v187
	s_cbranch_scc0 .LBB0_825
	s_mov_b32 s30, s29
	s_branch .LBB0_781

.LBB0_878:
	s_add_i32 s56, s56, 2
	s_addk_i32 s14, 0x4000
	s_add_u32 s74, s74, 0x40000
	s_addc_u32 s75, s75, 0
	s_add_i32 s31, s31, 2
	v_cvt_pk_bf16_f32 v176, v114, v115
	v_cvt_pk_bf16_f32 v177, v116, v117
	v_cvt_pk_bf16_f32 v178, v118, v119
	v_cvt_pk_bf16_f32 v179, v120, v121
	v_add_f32_e32 v213, v192, v122
	s_cmp_le_i32 s29, s71
	v_add_u32_e32 v185, 0x80, v185
	s_cbranch_scc0 .LBB0_890
	s_mov_b32 s30, s29
	s_branch .LBB0_849
